# phase-5 y stores as ordinary write-back stores instead of nontemporal
# speedup vs baseline: 1.0164x; 1.0082x over previous
.LBB0_1306:
	s_or_b64 exec, exec, s[0:1]
	v_readlane_b32 s0, v251, 5
	v_readlane_b32 s12, v251, 17
	v_readlane_b32 s13, v251, 18
	v_readlane_b32 s14, v251, 19
	v_readlane_b32 s15, v251, 20
	v_lshl_add_u64 v[2:3], s[12:13], 0, v[66:67]
	v_lshl_add_u64 v[38:39], v[136:137], 2, s[82:83]
	v_lshl_add_u64 v[6:7], s[14:15], 0, v[66:67]
	s_barrier
	global_load_dwordx4 v[26:29], v[2:3], off
	global_load_dwordx4 v[18:21], v[2:3], off offset:64
	global_load_dwordx4 v[30:33], v[6:7], off
	global_load_dwordx4 v[22:25], v[6:7], off offset:64
	global_load_dwordx4 v[10:13], v[2:3], off offset:512
	s_nop 0
	global_load_dwordx4 v[2:5], v[2:3], off offset:576
	s_nop 0
	global_load_dwordx4 v[14:17], v[6:7], off offset:512
	s_nop 0
	global_load_dwordx4 v[6:9], v[6:7], off offset:576
	s_nop 0
	global_load_dword v41, v[144:145], off sc1
	global_load_dword v40, v[144:145], off offset:4 sc1
	global_load_dword v141, v[38:39], off sc1
	global_load_dword v140, v[38:39], off offset:4 sc1
	v_lshl_add_u64 v[38:39], v[146:147], 2, s[82:83]
	global_load_dword v147, v[38:39], off sc1
	global_load_dword v146, v[38:39], off offset:4 sc1
	v_lshl_add_u64 v[38:39], v[156:157], 2, s[82:83]
	global_load_dword v157, v[38:39], off sc1
	global_load_dword v156, v[38:39], off offset:4 sc1
	v_lshl_add_u64 v[38:39], v[158:159], 2, s[82:83]
	global_load_dword v195, v[38:39], off sc1
	global_load_dword v194, v[38:39], off offset:4 sc1
	v_or_b32_e32 v144, 16, v152
	v_lshlrev_b32_e32 v38, 1, v144
	v_ashrrev_i32_e32 v39, 31, v38
	v_lshl_add_u64 v[38:39], v[38:39], 2, s[82:83]
	global_load_dword v197, v[38:39], off sc1
	global_load_dword v196, v[38:39], off offset:4 sc1
	v_or_b32_e32 v136, 32, v152
	v_or_b32_e32 v38, 48, v152
	v_lshlrev_b32_e32 v158, 1, v136
	v_lshlrev_b32_e32 v192, 1, v38
	v_ashrrev_i32_e32 v159, 31, v158
	v_ashrrev_i32_e32 v193, 31, v192
	v_lshl_add_u64 v[158:159], v[158:159], 2, s[82:83]
	v_lshl_add_u64 v[192:193], v[192:193], 2, s[82:83]
	global_load_dword v199, v[158:159], off sc1
	global_load_dword v198, v[158:159], off offset:4 sc1
	global_load_dword v201, v[192:193], off sc1
	global_load_dword v200, v[192:193], off offset:4 sc1
	v_readlane_b32 s2, v251, 7
	v_readlane_b32 s3, v251, 8
	s_mov_b32 s2, 0x3a800000
	s_mov_b32 s3, 0x800000
	v_readlane_b32 s8, v251, 13
	v_readlane_b32 s9, v251, 14
	s_mov_b32 s8, 0x3727c5ac
	v_readlane_b32 s1, v251, 6
	v_readlane_b32 s4, v251, 9
	v_readlane_b32 s5, v251, 10
	v_readlane_b32 s6, v251, 11
	v_readlane_b32 s7, v251, 12
	v_lshlrev_b64 v[68:69], 12, v[68:69]
	v_lshl_add_u64 v[68:69], s[84:85], 0, v[68:69]
	v_lshl_add_u64 v[68:69], v[68:69], 0, v[66:67]
	v_lshlrev_b64 v[134:135], 12, v[134:135]
	v_lshl_add_u64 v[134:135], s[84:85], 0, v[134:135]
	v_lshl_add_u64 v[134:135], v[134:135], 0, v[66:67]
	v_readlane_b32 s10, v251, 15
	v_readlane_b32 s11, v251, 16
	s_waitcnt vmcnt(14)
	v_pk_mul_f32 v[206:207], v[40:41], s[2:3] op_sel_hi:[1,0]
	s_waitcnt vmcnt(12)
	v_pk_mul_f32 v[208:209], v[140:141], s[2:3] op_sel_hi:[1,0]
	v_mov_b32_e32 v41, v207
	v_mov_b32_e32 v40, v209
	v_mov_b32_e32 v140, v208
	v_mov_b32_e32 v141, v206
	v_pk_fma_f32 v[40:41], v[40:41], v[40:41], v[140:141] neg_lo:[1,0,0] neg_hi:[1,0,0]
	s_waitcnt vmcnt(10)
	v_pk_mul_f32 v[192:193], v[146:147], s[2:3] op_sel_hi:[1,0]
	s_waitcnt vmcnt(8)
	v_pk_mul_f32 v[158:159], v[156:157], s[2:3] op_sel_hi:[1,0]
	v_pk_add_f32 v[40:41], v[40:41], s[8:9] op_sel_hi:[1,0]
	s_waitcnt vmcnt(6)
	v_pk_mul_f32 v[156:157], v[194:195], s[2:3] op_sel_hi:[1,0]
	v_mov_b32_e32 v146, v159
	v_mov_b32_e32 v147, v193
	v_mov_b32_e32 v194, v158
	v_mov_b32_e32 v195, v192
	v_mul_f32_e32 v137, 0x4b800000, v40
	v_cmp_gt_f32_e64 s[0:1], s3, v40
	v_pk_fma_f32 v[140:141], v[146:147], v[146:147], v[194:195] neg_lo:[1,0,0] neg_hi:[1,0,0]
	v_mul_f32_e32 v39, 0x4b800000, v41
	v_cndmask_b32_e64 v40, v40, v137, s[0:1]
	v_pk_add_f32 v[140:141], v[140:141], s[8:9] op_sel_hi:[1,0]
	v_rsq_f32_e32 v40, v40
	v_mul_f32_e32 v145, 0x4b800000, v141
	v_cmp_gt_f32_e32 vcc, s3, v41
	v_cmp_gt_f32_e64 s[4:5], s3, v141
	s_waitcnt vmcnt(4)
	v_pk_mul_f32 v[146:147], v[196:197], s[2:3] op_sel_hi:[1,0]
	v_cndmask_b32_e32 v39, v41, v39, vcc
	v_cndmask_b32_e64 v41, v141, v145, s[4:5]
	v_rsq_f32_e32 v39, v39
	v_rsq_f32_e32 v41, v41
	v_mul_f32_e32 v141, 0x45800000, v40
	v_cndmask_b32_e64 v196, v40, v141, s[0:1]
	v_sub_f32_e32 v117, v117, v209
	v_sub_f32_e32 v116, v116, v209
	v_sub_f32_e32 v115, v115, v209
	v_sub_f32_e32 v114, v114, v209
	v_sub_f32_e32 v113, v113, v209
	v_sub_f32_e32 v112, v112, v209
	v_sub_f32_e32 v111, v111, v209
	v_sub_f32_e32 v110, v110, v209
	v_sub_f32_e32 v109, v109, v209
	v_sub_f32_e32 v108, v108, v209
	v_sub_f32_e32 v107, v107, v209
	v_sub_f32_e32 v106, v106, v209
	v_sub_f32_e32 v105, v105, v209
	v_sub_f32_e32 v104, v104, v209
	v_sub_f32_e32 v103, v103, v209
	v_sub_f32_e32 v102, v102, v209
	v_mov_b32_e32 v213, v156
	v_mul_f32_e32 v156, 0x4b800000, v140
	v_cmp_gt_f32_e64 s[6:7], s3, v140
	v_pk_mul_f32 v[114:115], v[114:115], v[196:197] op_sel_hi:[1,0]
	v_pk_mul_f32 v[116:117], v[116:117], v[196:197] op_sel_hi:[1,0]
	v_pk_mul_f32 v[110:111], v[110:111], v[196:197] op_sel_hi:[1,0]
	v_pk_mul_f32 v[112:113], v[112:113], v[196:197] op_sel_hi:[1,0]
	v_pk_mul_f32 v[106:107], v[106:107], v[196:197] op_sel_hi:[1,0]
	v_pk_mul_f32 v[108:109], v[108:109], v[196:197] op_sel_hi:[1,0]
	v_pk_mul_f32 v[102:103], v[102:103], v[196:197] op_sel_hi:[1,0]
	v_pk_mul_f32 v[104:105], v[104:105], v[196:197] op_sel_hi:[1,0]
	v_cndmask_b32_e64 v137, v140, v156, s[6:7]
	v_mul_f32_e32 v140, 0x45800000, v39
	v_mul_f32_e32 v145, 0x45800000, v41
	v_pk_fma_f32 v[116:117], v[28:29], v[116:117], v[32:33]
	v_pk_fma_f32 v[114:115], v[26:27], v[114:115], v[30:31]
	v_pk_fma_f32 v[112:113], v[20:21], v[112:113], v[24:25]
	v_pk_fma_f32 v[110:111], v[18:19], v[110:111], v[22:23]
	v_pk_fma_f32 v[108:109], v[12:13], v[108:109], v[16:17]
	v_pk_fma_f32 v[106:107], v[10:11], v[106:107], v[14:15]
	v_pk_fma_f32 v[104:105], v[4:5], v[104:105], v[8:9]
	v_pk_fma_f32 v[102:103], v[2:3], v[102:103], v[6:7]
	v_rsq_f32_e32 v137, v137
	v_cndmask_b32_e32 v194, v39, v140, vcc
	v_cndmask_b32_e64 v192, v41, v145, s[4:5]
	v_sub_f32_e32 v133, v133, v207
	v_sub_f32_e32 v132, v132, v207
	v_sub_f32_e32 v131, v131, v207
	v_sub_f32_e32 v130, v130, v207
	v_sub_f32_e32 v129, v129, v207
	v_sub_f32_e32 v128, v128, v207
	v_sub_f32_e32 v127, v127, v207
	v_sub_f32_e32 v126, v126, v207
	v_sub_f32_e32 v125, v125, v207
	v_sub_f32_e32 v124, v124, v207
	v_sub_f32_e32 v123, v123, v207
	v_sub_f32_e32 v122, v122, v207
	v_sub_f32_e32 v121, v121, v207
	v_sub_f32_e32 v120, v120, v207
	v_sub_f32_e32 v119, v119, v207
	v_sub_f32_e32 v118, v118, v207
	global_store_dwordx4 v[68:69], v[114:117], off
	global_store_dwordx4 v[68:69], v[110:113], off offset:64
	global_store_dwordx4 v[68:69], v[106:109], off offset:512
	global_store_dwordx4 v[68:69], v[102:105], off offset:576
	v_lshlrev_b64 v[68:69], 12, v[138:139]
	v_sub_f32_e32 v101, v101, v193
	v_sub_f32_e32 v100, v100, v193
	v_sub_f32_e32 v99, v99, v193
	v_sub_f32_e32 v98, v98, v193
	v_sub_f32_e32 v97, v97, v193
	v_sub_f32_e32 v96, v96, v193
	v_sub_f32_e32 v95, v95, v193
	v_sub_f32_e32 v94, v94, v193
	v_sub_f32_e32 v93, v93, v193
	v_sub_f32_e32 v92, v92, v193
	v_sub_f32_e32 v91, v91, v193
	v_sub_f32_e32 v90, v90, v193
	v_sub_f32_e32 v89, v89, v193
	v_sub_f32_e32 v88, v88, v193
	v_sub_f32_e32 v87, v87, v193
	v_sub_f32_e32 v86, v86, v193
	v_pk_mul_f32 v[130:131], v[130:131], v[194:195] op_sel_hi:[1,0]
	v_pk_mul_f32 v[132:133], v[132:133], v[194:195] op_sel_hi:[1,0]
	v_pk_mul_f32 v[126:127], v[126:127], v[194:195] op_sel_hi:[1,0]
	v_pk_mul_f32 v[128:129], v[128:129], v[194:195] op_sel_hi:[1,0]
	v_pk_mul_f32 v[122:123], v[122:123], v[194:195] op_sel_hi:[1,0]
	v_pk_mul_f32 v[124:125], v[124:125], v[194:195] op_sel_hi:[1,0]
	v_pk_mul_f32 v[118:119], v[118:119], v[194:195] op_sel_hi:[1,0]
	v_pk_mul_f32 v[120:121], v[120:121], v[194:195] op_sel_hi:[1,0]
	v_pk_mul_f32 v[98:99], v[98:99], v[192:193] op_sel_hi:[1,0]
	v_pk_mul_f32 v[100:101], v[100:101], v[192:193] op_sel_hi:[1,0]
	v_lshl_add_u64 v[68:69], s[84:85], 0, v[68:69]
	v_pk_mul_f32 v[94:95], v[94:95], v[192:193] op_sel_hi:[1,0]
	v_pk_mul_f32 v[96:97], v[96:97], v[192:193] op_sel_hi:[1,0]
	v_pk_mul_f32 v[90:91], v[90:91], v[192:193] op_sel_hi:[1,0]
	v_pk_mul_f32 v[92:93], v[92:93], v[192:193] op_sel_hi:[1,0]
	v_pk_mul_f32 v[86:87], v[86:87], v[192:193] op_sel_hi:[1,0]
	v_pk_mul_f32 v[88:89], v[88:89], v[192:193] op_sel_hi:[1,0]
	v_mov_b32_e32 v211, v157
	v_mov_b32_e32 v210, v147
	v_mov_b32_e32 v212, v146
	v_pk_fma_f32 v[132:133], v[28:29], v[132:133], v[32:33]
	v_pk_fma_f32 v[130:131], v[26:27], v[130:131], v[30:31]
	v_pk_fma_f32 v[128:129], v[20:21], v[128:129], v[24:25]
	v_pk_fma_f32 v[126:127], v[18:19], v[126:127], v[22:23]
	v_pk_fma_f32 v[124:125], v[12:13], v[124:125], v[16:17]
	v_pk_fma_f32 v[122:123], v[10:11], v[122:123], v[14:15]
	v_pk_fma_f32 v[120:121], v[4:5], v[120:121], v[8:9]
	v_pk_fma_f32 v[118:119], v[2:3], v[118:119], v[6:7]
	v_pk_fma_f32 v[100:101], v[28:29], v[100:101], v[32:33]
	v_pk_fma_f32 v[98:99], v[26:27], v[98:99], v[30:31]
	v_lshl_add_u64 v[68:69], v[68:69], 0, v[66:67]
	v_pk_fma_f32 v[96:97], v[20:21], v[96:97], v[24:25]
	v_pk_fma_f32 v[94:95], v[18:19], v[94:95], v[22:23]
	v_pk_fma_f32 v[92:93], v[12:13], v[92:93], v[16:17]
	v_pk_fma_f32 v[90:91], v[10:11], v[90:91], v[14:15]
	v_pk_fma_f32 v[88:89], v[4:5], v[88:89], v[8:9]
	v_pk_fma_f32 v[86:87], v[2:3], v[86:87], v[6:7]
	v_pk_fma_f32 v[40:41], v[210:211], v[210:211], v[212:213] neg_lo:[1,0,0] neg_hi:[1,0,0]
	global_store_dwordx4 v[134:135], v[130:133], off
	global_store_dwordx4 v[134:135], v[126:129], off offset:64
	global_store_dwordx4 v[134:135], v[122:125], off offset:512
	global_store_dwordx4 v[134:135], v[118:121], off offset:576
	global_store_dwordx4 v[68:69], v[98:101], off
	global_store_dwordx4 v[68:69], v[94:97], off offset:64
	global_store_dwordx4 v[68:69], v[90:93], off offset:512
	global_store_dwordx4 v[68:69], v[86:89], off offset:576
	v_lshlrev_b64 v[68:69], 12, v[142:143]
	v_mul_f32_e32 v146, 0x45800000, v137
	v_pk_add_f32 v[40:41], v[40:41], s[8:9] op_sel_hi:[1,0]
	v_lshl_add_u64 v[68:69], s[84:85], 0, v[68:69]
	v_mul_f32_e32 v39, 0x4b800000, v41
	v_cmp_gt_f32_e32 vcc, s3, v41
	v_cndmask_b32_e64 v158, v137, v146, s[6:7]
	v_lshl_add_u64 v[86:87], v[68:69], 0, v[66:67]
	v_sub_f32_e32 v69, v81, v159
	v_sub_f32_e32 v68, v80, v159
	v_cndmask_b32_e32 v39, v41, v39, vcc
	v_pk_mul_f32 v[68:69], v[68:69], v[158:159] op_sel_hi:[1,0]
	v_rsq_f32_e32 v39, v39
	v_mul_f32_e32 v41, 0x4b800000, v40
	v_cmp_gt_f32_e64 s[0:1], s3, v40
	v_pk_fma_f32 v[80:81], v[20:21], v[68:69], v[24:25]
	v_sub_f32_e32 v69, v77, v159
	v_sub_f32_e32 v68, v76, v159
	v_cndmask_b32_e64 v40, v40, v41, s[0:1]
	v_pk_mul_f32 v[68:69], v[68:69], v[158:159] op_sel_hi:[1,0]
	v_rsq_f32_e32 v145, v40
	v_pk_fma_f32 v[76:77], v[12:13], v[68:69], v[16:17]
	v_sub_f32_e32 v69, v73, v159
	v_sub_f32_e32 v68, v72, v159
	v_sub_f32_e32 v71, v71, v159
	v_sub_f32_e32 v70, v70, v159
	v_pk_mul_f32 v[72:73], v[70:71], v[158:159] op_sel_hi:[1,0]
	v_pk_mul_f32 v[68:69], v[68:69], v[158:159] op_sel_hi:[1,0]
	v_mul_f32_e32 v40, 0x45800000, v39
	v_pk_fma_f32 v[70:71], v[4:5], v[68:69], v[8:9]
	v_pk_fma_f32 v[68:69], v[2:3], v[72:73], v[6:7]
	v_cndmask_b32_e32 v156, v39, v40, vcc
	v_sub_f32_e32 v75, v75, v159
	v_sub_f32_e32 v74, v74, v159
	global_store_dwordx4 v[86:87], v[68:71], off offset:576
	v_sub_f32_e32 v57, v57, v157
	v_sub_f32_e32 v56, v56, v157
	v_lshlrev_b64 v[68:69], 12, v[152:153]
	v_sub_f32_e32 v55, v55, v157
	v_sub_f32_e32 v54, v54, v157
	v_sub_f32_e32 v53, v53, v157
	v_sub_f32_e32 v52, v52, v157
	v_sub_f32_e32 v51, v51, v157
	v_sub_f32_e32 v50, v50, v157
	v_mul_f32_e32 v39, 0x45800000, v145
	v_pk_mul_f32 v[74:75], v[74:75], v[158:159] op_sel_hi:[1,0]
	v_lshl_add_u64 v[68:69], s[84:85], 0, v[68:69]
	v_pk_mul_f32 v[54:55], v[54:55], v[156:157] op_sel_hi:[1,0]
	v_pk_mul_f32 v[56:57], v[56:57], v[156:157] op_sel_hi:[1,0]
	v_pk_mul_f32 v[50:51], v[50:51], v[156:157] op_sel_hi:[1,0]
	v_pk_mul_f32 v[52:53], v[52:53], v[156:157] op_sel_hi:[1,0]
	s_waitcnt vmcnt(15)
	v_pk_mul_f32 v[140:141], v[198:199], s[2:3] op_sel_hi:[1,0]
	s_waitcnt vmcnt(13)
	v_pk_mul_f32 v[40:41], v[200:201], s[2:3] op_sel_hi:[1,0]
	v_cndmask_b32_e64 v146, v145, v39, s[0:1]
	v_pk_fma_f32 v[74:75], v[10:11], v[74:75], v[14:15]
	v_lshl_add_u64 v[68:69], v[68:69], 0, v[66:67]
	v_pk_fma_f32 v[56:57], v[12:13], v[56:57], v[16:17]
	v_pk_fma_f32 v[54:55], v[10:11], v[54:55], v[14:15]
	v_pk_fma_f32 v[52:53], v[4:5], v[52:53], v[8:9]
	v_pk_fma_f32 v[50:51], v[2:3], v[50:51], v[6:7]
	v_ashrrev_i32_e32 v145, 31, v144
	v_mov_b32_e32 v198, v41
	v_mov_b32_e32 v199, v141
	v_mov_b32_e32 v200, v40
	v_mov_b32_e32 v201, v140
	v_sub_f32_e32 v85, v85, v159
	v_sub_f32_e32 v84, v84, v159
	v_sub_f32_e32 v83, v83, v159
	v_sub_f32_e32 v82, v82, v159
	global_store_dwordx4 v[86:87], v[74:77], off offset:512
	v_sub_f32_e32 v65, v65, v157
	v_sub_f32_e32 v64, v64, v157
	v_sub_f32_e32 v63, v63, v157
	v_sub_f32_e32 v62, v62, v157
	global_store_dwordx4 v[68:69], v[54:57], off offset:512
	global_store_dwordx4 v[68:69], v[50:53], off offset:576
	v_pk_fma_f32 v[198:199], v[198:199], v[198:199], v[200:201] neg_lo:[1,0,0] neg_hi:[1,0,0]
	v_lshlrev_b64 v[54:55], 12, v[144:145]
	v_sub_f32_e32 v51, v173, v147
	v_sub_f32_e32 v50, v172, v147
	v_sub_f32_e32 v53, v171, v147
	v_sub_f32_e32 v52, v170, v147
	v_pk_mul_f32 v[82:83], v[82:83], v[158:159] op_sel_hi:[1,0]
	v_pk_mul_f32 v[84:85], v[84:85], v[158:159] op_sel_hi:[1,0]
	v_pk_mul_f32 v[62:63], v[62:63], v[156:157] op_sel_hi:[1,0]
	v_pk_mul_f32 v[64:65], v[64:65], v[156:157] op_sel_hi:[1,0]
	v_pk_mul_f32 v[56:57], v[52:53], v[146:147] op_sel_hi:[1,0]
	v_pk_mul_f32 v[50:51], v[50:51], v[146:147] op_sel_hi:[1,0]
	v_lshl_add_u64 v[54:55], s[84:85], 0, v[54:55]
	v_pk_add_f32 v[198:199], v[198:199], s[8:9] op_sel_hi:[1,0]
	v_pk_fma_f32 v[84:85], v[28:29], v[84:85], v[32:33]
	v_pk_fma_f32 v[82:83], v[26:27], v[82:83], v[30:31]
	v_pk_fma_f32 v[64:65], v[28:29], v[64:65], v[32:33]
	v_pk_fma_f32 v[62:63], v[26:27], v[62:63], v[30:31]
	v_pk_fma_f32 v[52:53], v[28:29], v[50:51], v[32:33]
	v_pk_fma_f32 v[50:51], v[26:27], v[56:57], v[30:31]
	v_lshl_add_u64 v[54:55], v[54:55], 0, v[66:67]
	v_mul_f32_e32 v40, 0x4b800000, v199
	v_cmp_gt_f32_e32 vcc, s3, v199
	global_store_dwordx4 v[86:87], v[82:85], off
	v_sub_f32_e32 v79, v79, v159
	v_sub_f32_e32 v78, v78, v159
	global_store_dwordx4 v[68:69], v[62:65], off
	v_sub_f32_e32 v61, v61, v157
	v_sub_f32_e32 v60, v60, v157
	v_sub_f32_e32 v59, v59, v157
	v_sub_f32_e32 v58, v58, v157
	global_store_dwordx4 v[54:55], v[50:53], off
	v_cndmask_b32_e32 v40, v199, v40, vcc
	v_mul_f32_e32 v137, 0x4b800000, v198
	v_sub_f32_e32 v51, v165, v147
	v_sub_f32_e32 v50, v164, v147
	v_sub_f32_e32 v53, v161, v147
	v_sub_f32_e32 v52, v160, v147
	v_cmp_gt_f32_e64 s[4:5], s3, v198
	v_pk_mul_f32 v[78:79], v[78:79], v[158:159] op_sel_hi:[1,0]
	v_pk_mul_f32 v[58:59], v[58:59], v[156:157] op_sel_hi:[1,0]
	v_pk_mul_f32 v[60:61], v[60:61], v[156:157] op_sel_hi:[1,0]
	v_pk_mul_f32 v[56:57], v[52:53], v[146:147] op_sel_hi:[1,0]
	v_pk_mul_f32 v[50:51], v[50:51], v[146:147] op_sel_hi:[1,0]
	v_rsq_f32_e32 v40, v40
	v_cndmask_b32_e64 v137, v198, v137, s[4:5]
	v_pk_fma_f32 v[78:79], v[18:19], v[78:79], v[22:23]
	v_pk_fma_f32 v[60:61], v[20:21], v[60:61], v[24:25]
	v_pk_fma_f32 v[58:59], v[18:19], v[58:59], v[22:23]
	v_pk_fma_f32 v[52:53], v[20:21], v[50:51], v[24:25]
	v_pk_fma_f32 v[50:51], v[18:19], v[56:57], v[22:23]
	v_rsq_f32_e32 v137, v137
	global_store_dwordx4 v[86:87], v[78:81], off offset:64
	global_store_dwordx4 v[68:69], v[58:61], off offset:64
	global_store_dwordx4 v[54:55], v[50:53], off offset:64
	v_mul_f32_e32 v39, 0x45800000, v40
	v_cndmask_b32_e32 v140, v40, v39, vcc
	v_sub_f32_e32 v51, v169, v147
	v_sub_f32_e32 v50, v168, v147
	v_sub_f32_e32 v53, v167, v147
	v_sub_f32_e32 v52, v166, v147
	v_pk_mul_f32 v[56:57], v[52:53], v[146:147] op_sel_hi:[1,0]
	v_pk_mul_f32 v[50:51], v[50:51], v[146:147] op_sel_hi:[1,0]
	v_mul_f32_e32 v39, 0x45800000, v137
	v_pk_fma_f32 v[52:53], v[12:13], v[50:51], v[16:17]
	v_pk_fma_f32 v[50:51], v[10:11], v[56:57], v[14:15]
	global_store_dwordx4 v[54:55], v[50:53], off offset:512
	v_cndmask_b32_e64 v40, v137, v39, s[4:5]
	v_ashrrev_i32_e32 v137, 31, v136
	v_sub_f32_e32 v51, v177, v147
	v_sub_f32_e32 v50, v176, v147
	v_sub_f32_e32 v53, v175, v147
	v_sub_f32_e32 v52, v174, v147
	v_pk_mul_f32 v[56:57], v[52:53], v[146:147] op_sel_hi:[1,0]
	v_pk_mul_f32 v[50:51], v[50:51], v[146:147] op_sel_hi:[1,0]
	v_ashrrev_i32_e32 v39, 31, v38
	v_pk_fma_f32 v[52:53], v[4:5], v[50:51], v[8:9]
	v_pk_fma_f32 v[50:51], v[2:3], v[56:57], v[6:7]
	global_store_dwordx4 v[54:55], v[50:53], off offset:576
	v_lshlrev_b64 v[54:55], 12, v[136:137]
	v_lshl_add_u64 v[54:55], s[84:85], 0, v[54:55]
	v_sub_f32_e32 v51, v187, v141
	v_sub_f32_e32 v50, v186, v141
	v_sub_f32_e32 v53, v185, v141
	v_sub_f32_e32 v52, v184, v141
	v_pk_mul_f32 v[56:57], v[52:53], v[140:141] op_sel_hi:[1,0]
	v_pk_mul_f32 v[50:51], v[50:51], v[140:141] op_sel_hi:[1,0]
	v_lshl_add_u64 v[54:55], v[54:55], 0, v[66:67]
	v_pk_fma_f32 v[52:53], v[28:29], v[50:51], v[32:33]
	v_pk_fma_f32 v[50:51], v[26:27], v[56:57], v[30:31]
	global_store_dwordx4 v[54:55], v[50:53], off
	v_lshlrev_b64 v[38:39], 12, v[38:39]
	s_nop 0
	v_sub_f32_e32 v51, v179, v141
	v_sub_f32_e32 v50, v178, v141
	v_sub_f32_e32 v53, v155, v141
	v_sub_f32_e32 v52, v154, v141
	v_pk_mul_f32 v[56:57], v[52:53], v[140:141] op_sel_hi:[1,0]
	v_pk_mul_f32 v[50:51], v[50:51], v[140:141] op_sel_hi:[1,0]
	s_nop 0
	v_pk_fma_f32 v[52:53], v[20:21], v[50:51], v[24:25]
	v_pk_fma_f32 v[50:51], v[18:19], v[56:57], v[22:23]
	global_store_dwordx4 v[54:55], v[50:53], off offset:64
	s_nop 1
	v_sub_f32_e32 v51, v183, v141
	v_sub_f32_e32 v50, v182, v141
	v_sub_f32_e32 v53, v181, v141
	v_sub_f32_e32 v52, v180, v141
	v_pk_mul_f32 v[56:57], v[52:53], v[140:141] op_sel_hi:[1,0]
	v_pk_mul_f32 v[50:51], v[50:51], v[140:141] op_sel_hi:[1,0]
	s_nop 0
	v_pk_fma_f32 v[52:53], v[12:13], v[50:51], v[16:17]
	v_pk_fma_f32 v[50:51], v[10:11], v[56:57], v[14:15]
	global_store_dwordx4 v[54:55], v[50:53], off offset:512
	s_nop 1
	v_sub_f32_e32 v51, v191, v141
	v_sub_f32_e32 v50, v190, v141
	v_sub_f32_e32 v53, v189, v141
	v_sub_f32_e32 v52, v188, v141
	v_pk_mul_f32 v[56:57], v[52:53], v[140:141] op_sel_hi:[1,0]
	v_pk_mul_f32 v[50:51], v[50:51], v[140:141] op_sel_hi:[1,0]
	s_nop 0
	v_pk_fma_f32 v[52:53], v[4:5], v[50:51], v[8:9]
	v_pk_fma_f32 v[50:51], v[2:3], v[56:57], v[6:7]
	global_store_dwordx4 v[54:55], v[50:53], off offset:576
	s_nop 1
	v_sub_f32_e32 v53, v149, v41
	v_sub_f32_e32 v52, v148, v41
	v_sub_f32_e32 v51, v151, v41
	v_sub_f32_e32 v50, v150, v41
	v_pk_mul_f32 v[52:53], v[52:53], v[40:41] op_sel_hi:[1,0]
	v_pk_mul_f32 v[50:51], v[50:51], v[40:41] op_sel_hi:[1,0]
	v_pk_fma_f32 v[26:27], v[26:27], v[52:53], v[30:31]
	v_lshl_add_u64 v[30:31], s[84:85], 0, v[38:39]
	v_pk_fma_f32 v[28:29], v[28:29], v[50:51], v[32:33]
	v_lshl_add_u64 v[30:31], v[30:31], 0, v[66:67]
	global_store_dwordx4 v[30:31], v[26:29], off
	s_nop 1
	v_sub_f32_e32 v27, v49, v41
	v_sub_f32_e32 v26, v48, v41
	v_sub_f32_e32 v29, v47, v41
	v_sub_f32_e32 v28, v46, v41
	v_pk_mul_f32 v[28:29], v[28:29], v[40:41] op_sel_hi:[1,0]
	v_pk_mul_f32 v[26:27], v[26:27], v[40:41] op_sel_hi:[1,0]
	v_pk_fma_f32 v[18:19], v[18:19], v[28:29], v[22:23]
	v_pk_fma_f32 v[20:21], v[20:21], v[26:27], v[24:25]
	global_store_dwordx4 v[30:31], v[18:21], off offset:64
	s_nop 1
	v_sub_f32_e32 v19, v45, v41
	v_sub_f32_e32 v18, v44, v41
	v_sub_f32_e32 v21, v43, v41
	v_sub_f32_e32 v20, v42, v41
	v_pk_mul_f32 v[20:21], v[20:21], v[40:41] op_sel_hi:[1,0]
	v_pk_mul_f32 v[18:19], v[18:19], v[40:41] op_sel_hi:[1,0]
	v_pk_fma_f32 v[10:11], v[10:11], v[20:21], v[14:15]
	v_pk_fma_f32 v[12:13], v[12:13], v[18:19], v[16:17]
	global_store_dwordx4 v[30:31], v[10:13], off offset:512
	s_nop 1
	v_sub_f32_e32 v11, v37, v41
	v_sub_f32_e32 v10, v36, v41
	v_sub_f32_e32 v13, v35, v41
	v_sub_f32_e32 v12, v34, v41
	v_pk_mul_f32 v[12:13], v[12:13], v[40:41] op_sel_hi:[1,0]
	v_pk_mul_f32 v[10:11], v[10:11], v[40:41] op_sel_hi:[1,0]
	v_pk_fma_f32 v[2:3], v[2:3], v[12:13], v[6:7]
	v_pk_fma_f32 v[4:5], v[4:5], v[10:11], v[8:9]
	global_store_dwordx4 v[30:31], v[2:5], off offset:576
